# pcmp unit K-loop: all 16 W1 fragment loads of a K chunk issued together with counted waits (were requested at most 3 ahead), A fragments read one k-step ahead
# speedup vs baseline: 1.0120x; 1.0087x over previous
; #define LAS __attribute__((address_space(3)))
; DI void pcmp_unit(const Args& a, LAS unsigned char* lds, int kind, int seq, int quarter, int wave, int lane) {
;     ...
;     for (int kc = 0; kc < 8; ++kc) {
;         LAS unsigned char* abuf = lds + 65536 + (kc & 1) * 32768;
; #pragma unroll
;         for (int i = 0; i < 2; ++i) { const int idx = tid + 512 * i, rw = idx >> 5, ch = idx & 31; *(LAS u32x4*)(abuf + paoff(rw, ch)) = areg[i]; }
;         __syncthreads();
;         if (kc + 1 < 8) {
; #pragma unroll
;             for (int i = 0; i < 2; ++i) { const int idx = tid + 512 * i, rw = idx >> 5, ch = idx & 31; areg[i] = *(const u32x4*)(Ab + (size_t)rw * 1024 + (kc + 1) * 256 + ch * 8); } }
;         bf16x8 bfr[8][2];
; #pragma unroll
;         for (int ks = 0; ks < 8; ++ks)
; #pragma unroll
;             for (int nt = 0; nt < 2; ++nt) bfr[ks][nt] = *(const bf16x8*)(B + (size_t)nt * 16 * 2048 + kc * 256 + 32 * ks);
; #pragma unroll
;         for (int ks = 0; ks < 8; ++ks)
; #pragma unroll
;             for (int mt = 0; mt < 2; ++mt) { const bf16x8 af = *(const LAS bf16x8*)(abuf + paoff(16 * mt + fr, 4 * ks + fq));
; #pragma unroll
;                 for (int nt = 0; nt < 2; ++nt) acc[mt][nt] = __builtin_amdgcn_mfma_f32_16x16x32_bf16(af, bfr[ks][nt], acc[mt][nt], 0, 0, 0); }
.LBB0_1302:
	v_lshl_add_u64 v[88:89], v[46:47], 0, s[4:5]
	v_add_co_u32_e32 v96, vcc, 0x2080000, v88
	v_add_u32_e32 v100, s12, v28
	s_nop 0
	v_addc_co_u32_e32 v97, vcc, 0, v89, vcc
	v_add_co_u32_e32 v98, vcc, 0x2090000, v88
	s_nop 1
	v_addc_co_u32_e32 v99, vcc, 0, v89, vcc
	global_load_dwordx4 v[132:135], v[96:97], off
	global_load_dwordx4 v[136:139], v[98:99], off
	global_load_dwordx4 v[140:143], v[96:97], off offset:64
	global_load_dwordx4 v[144:147], v[98:99], off offset:64
	global_load_dwordx4 v[148:151], v[96:97], off offset:128
	global_load_dwordx4 v[152:155], v[98:99], off offset:128
	global_load_dwordx4 v[160:163], v[96:97], off offset:192
	global_load_dwordx4 v[168:171], v[98:99], off offset:192
	global_load_dwordx4 v[172:175], v[96:97], off offset:256
	global_load_dwordx4 v[176:179], v[98:99], off offset:256
	global_load_dwordx4 v[180:183], v[96:97], off offset:320
	global_load_dwordx4 v[188:191], v[98:99], off offset:320
	global_load_dwordx4 v[192:195], v[96:97], off offset:384
	global_load_dwordx4 v[196:199], v[98:99], off offset:384
	global_load_dwordx4 v[200:203], v[96:97], off offset:448
	global_load_dwordx4 v[204:207], v[98:99], off offset:448
	v_add_u32_e32 v101, v100, v52
	ds_read_b128 v[76:79], v101
	ds_read_b128 v[84:87], v101 offset:8192
	s_add_u32 s4, s4, 0x200
	s_addc_u32 s5, s5, 0
	s_add_i32 s7, s7, 0x8000
	s_cmpk_lg_i32 s4, 0x1000
	v_add_u32_e32 v101, v100, v53
	ds_read_b128 v[80:83], v101
	ds_read_b128 v[88:91], v101 offset:8192
	s_waitcnt vmcnt(14) lgkmcnt(2)
	v_mfma_f32_16x16x32_bf16 v[22:25], v[76:79], v[132:135], v[22:25]
	v_mfma_f32_16x16x32_bf16 v[6:9], v[84:87], v[132:135], v[6:9]
	v_mfma_f32_16x16x32_bf16 v[18:21], v[76:79], v[136:139], v[18:21]
	v_mfma_f32_16x16x32_bf16 v[2:5], v[84:87], v[136:139], v[2:5]
	v_add_u32_e32 v101, v100, v54
	ds_read_b128 v[76:79], v101
	ds_read_b128 v[84:87], v101 offset:8192
	s_waitcnt vmcnt(12) lgkmcnt(2)
	v_mfma_f32_16x16x32_bf16 v[22:25], v[80:83], v[140:143], v[22:25]
	v_mfma_f32_16x16x32_bf16 v[6:9], v[88:91], v[140:143], v[6:9]
	v_mfma_f32_16x16x32_bf16 v[18:21], v[80:83], v[144:147], v[18:21]
	v_mfma_f32_16x16x32_bf16 v[2:5], v[88:91], v[144:147], v[2:5]
	v_add_u32_e32 v101, v100, v55
	ds_read_b128 v[80:83], v101
	ds_read_b128 v[88:91], v101 offset:8192
	s_waitcnt vmcnt(10) lgkmcnt(2)
	v_mfma_f32_16x16x32_bf16 v[22:25], v[76:79], v[148:151], v[22:25]
	v_mfma_f32_16x16x32_bf16 v[6:9], v[84:87], v[148:151], v[6:9]
	v_mfma_f32_16x16x32_bf16 v[18:21], v[76:79], v[152:155], v[18:21]
	v_mfma_f32_16x16x32_bf16 v[2:5], v[84:87], v[152:155], v[2:5]
	v_add_u32_e32 v101, v100, v66
	ds_read_b128 v[76:79], v101
	ds_read_b128 v[84:87], v101 offset:8192
	s_waitcnt vmcnt(8) lgkmcnt(2)
	v_mfma_f32_16x16x32_bf16 v[22:25], v[80:83], v[160:163], v[22:25]
	v_mfma_f32_16x16x32_bf16 v[6:9], v[88:91], v[160:163], v[6:9]
	v_mfma_f32_16x16x32_bf16 v[18:21], v[80:83], v[168:171], v[18:21]
	v_mfma_f32_16x16x32_bf16 v[2:5], v[88:91], v[168:171], v[2:5]
	v_add_u32_e32 v101, v100, v67
	ds_read_b128 v[80:83], v101
	ds_read_b128 v[88:91], v101 offset:8192
	s_waitcnt vmcnt(6) lgkmcnt(2)
	v_mfma_f32_16x16x32_bf16 v[22:25], v[76:79], v[172:175], v[22:25]
	v_mfma_f32_16x16x32_bf16 v[6:9], v[84:87], v[172:175], v[6:9]
	v_mfma_f32_16x16x32_bf16 v[18:21], v[76:79], v[176:179], v[18:21]
	v_mfma_f32_16x16x32_bf16 v[2:5], v[84:87], v[176:179], v[2:5]
	v_add_u32_e32 v101, v100, v68
	ds_read_b128 v[76:79], v101
	ds_read_b128 v[84:87], v101 offset:8192
	s_waitcnt vmcnt(4) lgkmcnt(2)
	v_mfma_f32_16x16x32_bf16 v[22:25], v[80:83], v[180:183], v[22:25]
	v_mfma_f32_16x16x32_bf16 v[6:9], v[88:91], v[180:183], v[6:9]
	v_mfma_f32_16x16x32_bf16 v[18:21], v[80:83], v[188:191], v[18:21]
	v_mfma_f32_16x16x32_bf16 v[2:5], v[88:91], v[188:191], v[2:5]
	v_add_u32_e32 v101, v100, v69
	ds_read_b128 v[80:83], v101
	ds_read_b128 v[88:91], v101 offset:8192
	s_waitcnt vmcnt(2) lgkmcnt(2)
	v_mfma_f32_16x16x32_bf16 v[22:25], v[76:79], v[192:195], v[22:25]
	v_mfma_f32_16x16x32_bf16 v[6:9], v[84:87], v[192:195], v[6:9]
	v_mfma_f32_16x16x32_bf16 v[18:21], v[76:79], v[196:199], v[18:21]
	v_mfma_f32_16x16x32_bf16 v[2:5], v[84:87], v[196:199], v[2:5]
	s_waitcnt vmcnt(0) lgkmcnt(0)
	v_mfma_f32_16x16x32_bf16 v[22:25], v[80:83], v[200:203], v[22:25]
	v_mfma_f32_16x16x32_bf16 v[6:9], v[88:91], v[200:203], v[6:9]
	v_mfma_f32_16x16x32_bf16 v[18:21], v[80:83], v[204:207], v[18:21]
	v_mfma_f32_16x16x32_bf16 v[2:5], v[88:91], v[204:207], v[2:5]
	s_cbranch_scc0 .LBB0_1305
